# b8 + accumulator reset with 64-bit moves at GEMM unit starts
# speedup vs baseline: 1.0124x; 1.0062x over previous
.LBB0_190:
	s_mov_b32 s61, s52
	s_add_i32 s52, s52, 1
	s_mov_b32 s59, s14
	s_lshr_b32 s14, s52, 3
	s_mul_i32 s14, s14, s48
	s_add_i32 s14, s14, s41
	s_cmp_lt_i32 s14, 32
	s_mov_b32 s60, s18
	s_cselect_b64 s[30:31], -1, 0
	s_lshl_b32 s18, s14, 3
	s_and_b32 s18, s18, 24
	s_add_i32 s18, s18, s42
	s_and_b32 s15, s52, 7
	s_lshl_b32 s18, s18, 3
	s_or_b32 s18, s18, s15
	s_ashr_i32 s19, s18, 31
	s_mov_b64 s[34:35], s[20:21]
	s_ashr_i32 s14, s14, 2
	s_lshl_b64 s[20:21], s[18:19], 19
	s_mov_b64 s[8:9], s[22:23]
	s_add_u32 s22, s64, s20
	s_addc_u32 s23, s65, s21
	s_and_b64 s[20:21], s[30:31], exec
	s_cselect_b32 s62, s23, s9
	s_cselect_b32 s63, s22, s8
	s_ashr_i32 s15, s14, 31
	s_lshl_b64 s[20:21], s[14:15], 19
	v_readlane_b32 s36, v235, 29
	v_readlane_b32 s37, v235, 30
	s_add_u32 s20, s36, s20
	s_addc_u32 s21, s37, s21
	s_and_b64 s[36:37], s[30:31], exec
	s_cselect_b32 s15, s21, s35
	s_cselect_b32 s67, s20, s34
	s_add_u32 s68, s34, 0x100
	v_mov_b32_e32 v60, 0
	s_addc_u32 s69, s35, 0
	s_mov_b32 s70, -2
	v_mov_b32_e32 v61, v60
	v_mov_b64_e32 v[62:63], 0
	v_mov_b64_e32 v[68:69], 0
	v_mov_b64_e32 v[70:71], 0
	v_mov_b64_e32 v[80:81], 0
	v_mov_b64_e32 v[82:83], 0
	v_mov_b64_e32 v[88:89], 0
	v_mov_b64_e32 v[90:91], 0
	v_mov_b64_e32 v[0:1], 0
	v_mov_b64_e32 v[2:3], 0
	v_mov_b64_e32 v[32:33], 0
	v_mov_b64_e32 v[34:35], 0
	v_mov_b64_e32 v[4:5], 0
	v_mov_b64_e32 v[6:7], 0
	v_mov_b64_e32 v[36:37], 0
	v_mov_b64_e32 v[38:39], 0
	v_mov_b64_e32 v[76:77], 0
	v_mov_b64_e32 v[78:79], 0
	v_mov_b64_e32 v[84:85], 0
	v_mov_b64_e32 v[86:87], 0
	v_mov_b64_e32 v[92:93], 0
	v_mov_b64_e32 v[94:95], 0
	v_mov_b64_e32 v[96:97], 0
	v_mov_b64_e32 v[98:99], 0
	v_mov_b64_e32 v[8:9], 0
	v_mov_b64_e32 v[10:11], 0
	v_mov_b64_e32 v[40:41], 0
	v_mov_b64_e32 v[42:43], 0
	v_mov_b64_e32 v[12:13], 0
	v_mov_b64_e32 v[14:15], 0
	v_mov_b64_e32 v[44:45], 0
	v_mov_b64_e32 v[46:47], 0
	v_mov_b64_e32 v[100:101], 0
	v_mov_b64_e32 v[102:103], 0
	v_mov_b64_e32 v[104:105], 0
	v_mov_b64_e32 v[106:107], 0
	v_mov_b64_e32 v[108:109], 0
	v_mov_b64_e32 v[110:111], 0
	v_mov_b64_e32 v[112:113], 0
	v_mov_b64_e32 v[114:115], 0
	v_mov_b64_e32 v[16:17], 0
	v_mov_b64_e32 v[18:19], 0
	v_mov_b64_e32 v[52:53], 0
	v_mov_b64_e32 v[54:55], 0
	v_mov_b64_e32 v[20:21], 0
	v_mov_b64_e32 v[22:23], 0
	v_mov_b64_e32 v[56:57], 0
	v_mov_b64_e32 v[58:59], 0
	v_mov_b64_e32 v[116:117], 0
	v_mov_b64_e32 v[118:119], 0
	v_mov_b64_e32 v[120:121], 0
	v_mov_b64_e32 v[122:123], 0
	v_mov_b64_e32 v[124:125], 0
	v_mov_b64_e32 v[126:127], 0
	v_mov_b64_e32 v[128:129], 0
	v_mov_b64_e32 v[130:131], 0
	v_mov_b64_e32 v[24:25], 0
	v_mov_b64_e32 v[26:27], 0
	v_mov_b64_e32 v[64:65], 0
	v_mov_b64_e32 v[66:67], 0
	v_mov_b64_e32 v[28:29], 0
	v_mov_b64_e32 v[30:31], 0
	v_mov_b64_e32 v[72:73], 0
	v_mov_b64_e32 v[74:75], 0
	v_readlane_b32 s38, v235, 31
	v_readlane_b32 s39, v235, 32

.LBB0_285:
	s_ashr_i32 s23, s22, 31
	v_cmp_lt_i64_e32 vcc, s[24:25], v[144:145]
	s_lshl_b64 s[24:25], s[22:23], 19
	s_add_u32 s24, s64, s24
	s_addc_u32 s25, s65, s25
	s_and_b64 s[28:29], vcc, exec
	s_cselect_b32 s23, s25, s35
	s_cselect_b32 s55, s24, s34
	s_ashr_i32 s21, s20, 31
	s_lshl_b64 s[28:29], s[20:21], 19
	s_add_u32 s28, s42, s28
	s_addc_u32 s29, s43, s29
	s_and_b64 s[38:39], vcc, exec
	s_cselect_b32 s21, s29, s37
	s_cselect_b32 s56, s28, s36
	s_add_u32 s34, s34, 0x40080
	s_addc_u32 s35, s35, 0
	s_add_u32 s57, s36, 0x100
	v_mov_b32_e32 v0, 0
	s_addc_u32 s58, s37, 0
	s_mov_b32 s59, -2
	v_mov_b32_e32 v1, v0
	v_mov_b32_e32 v2, v0
	v_mov_b32_e32 v3, v0
	v_mov_b32_e32 v4, v0
	v_mov_b32_e32 v5, v0
	v_mov_b32_e32 v6, v0
	v_mov_b32_e32 v7, v0
	s_waitcnt lgkmcnt(0)
	v_mov_b64_e32 v[16:17], 0
	v_mov_b64_e32 v[18:19], 0
	v_mov_b64_e32 v[20:21], 0
	v_mov_b64_e32 v[22:23], 0
	v_mov_b64_e32 v[32:33], 0
	v_mov_b64_e32 v[34:35], 0
	v_mov_b64_e32 v[36:37], 0
	v_mov_b64_e32 v[38:39], 0
	v_mov_b64_e32 v[48:49], 0
	v_mov_b64_e32 v[50:51], 0
	v_mov_b64_e32 v[52:53], 0
	v_mov_b64_e32 v[54:55], 0
	v_mov_b64_e32 v[8:9], 0
	v_mov_b64_e32 v[10:11], 0
	v_mov_b64_e32 v[12:13], 0
	v_mov_b64_e32 v[14:15], 0
	v_mov_b64_e32 v[24:25], 0
	v_mov_b64_e32 v[26:27], 0
	v_mov_b64_e32 v[28:29], 0
	v_mov_b64_e32 v[30:31], 0
	v_mov_b64_e32 v[40:41], 0
	v_mov_b64_e32 v[42:43], 0
	v_mov_b64_e32 v[44:45], 0
	v_mov_b64_e32 v[46:47], 0
	v_mov_b64_e32 v[56:57], 0
	v_mov_b64_e32 v[58:59], 0
	v_mov_b64_e32 v[60:61], 0
	v_mov_b64_e32 v[62:63], 0
	v_mov_b64_e32 v[64:65], 0
	v_mov_b64_e32 v[66:67], 0
	v_mov_b64_e32 v[68:69], 0
	v_mov_b64_e32 v[70:71], 0
	v_mov_b64_e32 v[80:81], 0
	v_mov_b64_e32 v[82:83], 0
	v_mov_b64_e32 v[84:85], 0
	v_mov_b64_e32 v[86:87], 0
	v_mov_b64_e32 v[96:97], 0
	v_mov_b64_e32 v[98:99], 0
	v_mov_b64_e32 v[100:101], 0
	v_mov_b64_e32 v[102:103], 0
	v_mov_b64_e32 v[112:113], 0
	v_mov_b64_e32 v[114:115], 0
	v_mov_b64_e32 v[116:117], 0
	v_mov_b64_e32 v[118:119], 0
	v_mov_b64_e32 v[72:73], 0
	v_mov_b64_e32 v[74:75], 0
	v_mov_b64_e32 v[76:77], 0
	v_mov_b64_e32 v[78:79], 0
	v_mov_b64_e32 v[88:89], 0
	v_mov_b64_e32 v[90:91], 0
	v_mov_b64_e32 v[92:93], 0
	v_mov_b64_e32 v[94:95], 0
	v_mov_b64_e32 v[104:105], 0
	v_mov_b64_e32 v[106:107], 0
	v_mov_b64_e32 v[108:109], 0
	v_mov_b64_e32 v[110:111], 0
	v_mov_b64_e32 v[120:121], 0
	v_mov_b64_e32 v[122:123], 0
	v_mov_b64_e32 v[124:125], 0
	v_mov_b64_e32 v[126:127], 0

.LBB0_363:
	s_ashr_i32 s13, s12, 31
	v_cmp_lt_i64_e32 vcc, s[14:15], v[190:191]
	s_lshl_b64 s[14:15], s[12:13], 19
	s_add_u32 s14, s26, s14
	s_addc_u32 s15, s27, s15
	s_and_b64 s[18:19], vcc, exec
	s_cselect_b32 s13, s15, s23
	s_cselect_b32 s21, s14, s22
	s_ashr_i32 s11, s10, 31
	s_lshl_b64 s[18:19], s[10:11], 19
	s_add_u32 s18, s31, s18
	s_addc_u32 s19, s34, s19
	s_and_b64 s[28:29], vcc, exec
	s_cselect_b32 s11, s19, s25
	s_cselect_b32 s48, s18, s24
	s_add_u32 s22, s22, 0x40080
	s_addc_u32 s23, s23, 0
	s_add_u32 s49, s24, 0x100
	v_mov_b32_e32 v0, 0
	s_addc_u32 s50, s25, 0
	s_mov_b32 s51, -2
	s_waitcnt lgkmcnt(0)
	v_mov_b32_e32 v1, v0
	v_mov_b32_e32 v2, v0
	v_mov_b32_e32 v3, v0
	v_mov_b32_e32 v4, v0
	v_mov_b32_e32 v5, v0
	v_mov_b32_e32 v6, v0
	v_mov_b32_e32 v7, v0
	s_waitcnt lgkmcnt(0)
	v_mov_b32_e32 v16, v0
	v_mov_b32_e32 v17, v0
	v_mov_b32_e32 v18, v0
	v_mov_b32_e32 v19, v0
	v_mov_b32_e32 v20, v0
	v_mov_b32_e32 v21, v0
	v_mov_b32_e32 v22, v0
	v_mov_b32_e32 v23, v0
	v_mov_b32_e32 v32, v0
	v_mov_b32_e32 v33, v0
	v_mov_b32_e32 v34, v0
	v_mov_b32_e32 v35, v0
	v_mov_b32_e32 v36, v0
	v_mov_b32_e32 v37, v0
	v_mov_b32_e32 v38, v0
	v_mov_b32_e32 v39, v0
	s_waitcnt vmcnt(0)
	v_mov_b64_e32 v[48:49], 0
	v_mov_b64_e32 v[50:51], 0
	v_mov_b64_e32 v[52:53], 0
	v_mov_b64_e32 v[54:55], 0
	v_mov_b64_e32 v[8:9], 0
	v_mov_b64_e32 v[10:11], 0
	v_mov_b64_e32 v[12:13], 0
	v_mov_b64_e32 v[14:15], 0
	v_mov_b64_e32 v[24:25], 0
	v_mov_b64_e32 v[26:27], 0
	v_mov_b64_e32 v[28:29], 0
	v_mov_b64_e32 v[30:31], 0
	v_mov_b64_e32 v[40:41], 0
	v_mov_b64_e32 v[42:43], 0
	v_mov_b64_e32 v[44:45], 0
	v_mov_b64_e32 v[46:47], 0
	v_mov_b64_e32 v[56:57], 0
	v_mov_b64_e32 v[58:59], 0
	v_mov_b64_e32 v[60:61], 0
	v_mov_b64_e32 v[62:63], 0
	v_mov_b64_e32 v[64:65], 0
	v_mov_b64_e32 v[66:67], 0
	v_mov_b64_e32 v[68:69], 0
	v_mov_b64_e32 v[70:71], 0
	v_mov_b64_e32 v[80:81], 0
	v_mov_b64_e32 v[82:83], 0
	v_mov_b64_e32 v[84:85], 0
	v_mov_b64_e32 v[86:87], 0
	v_mov_b64_e32 v[96:97], 0
	v_mov_b64_e32 v[98:99], 0
	v_mov_b64_e32 v[100:101], 0
	v_mov_b64_e32 v[102:103], 0
	v_mov_b64_e32 v[112:113], 0
	v_mov_b64_e32 v[114:115], 0
	v_mov_b64_e32 v[116:117], 0
	v_mov_b64_e32 v[118:119], 0
	v_mov_b64_e32 v[72:73], 0
	v_mov_b64_e32 v[74:75], 0
	v_mov_b64_e32 v[76:77], 0
	v_mov_b64_e32 v[78:79], 0
	v_mov_b64_e32 v[88:89], 0
	v_mov_b64_e32 v[90:91], 0
	v_mov_b64_e32 v[92:93], 0
	v_mov_b64_e32 v[94:95], 0
	v_mov_b64_e32 v[104:105], 0
	v_mov_b64_e32 v[106:107], 0
	v_mov_b64_e32 v[108:109], 0
	v_mov_b64_e32 v[110:111], 0
	v_mov_b64_e32 v[120:121], 0
	v_mov_b64_e32 v[122:123], 0
	v_mov_b64_e32 v[124:125], 0
	v_mov_b64_e32 v[126:127], 0

.LBB0_553:
	s_add_u32 s49, s18, 0x100
	v_mov_b32_e32 v0, 0
	s_addc_u32 s50, s19, 0
	s_mov_b32 s51, -2
	s_waitcnt lgkmcnt(0)
	v_mov_b32_e32 v1, v0
	v_mov_b64_e32 v[2:3], 0
	v_mov_b64_e32 v[4:5], 0
	v_mov_b64_e32 v[6:7], 0
	v_mov_b64_e32 v[16:17], 0
	v_mov_b64_e32 v[18:19], 0
	v_mov_b64_e32 v[20:21], 0
	v_mov_b64_e32 v[22:23], 0
	v_mov_b64_e32 v[32:33], 0
	v_mov_b64_e32 v[34:35], 0
	v_mov_b64_e32 v[36:37], 0
	v_mov_b64_e32 v[38:39], 0
	v_mov_b64_e32 v[48:49], 0
	v_mov_b64_e32 v[50:51], 0
	v_mov_b64_e32 v[52:53], 0
	v_mov_b64_e32 v[54:55], 0
	v_mov_b64_e32 v[8:9], 0
	v_mov_b64_e32 v[10:11], 0
	v_mov_b64_e32 v[12:13], 0
	v_mov_b64_e32 v[14:15], 0
	v_mov_b64_e32 v[24:25], 0
	v_mov_b64_e32 v[26:27], 0
	v_mov_b64_e32 v[28:29], 0
	v_mov_b64_e32 v[30:31], 0
	v_mov_b64_e32 v[40:41], 0
	v_mov_b64_e32 v[42:43], 0
	v_mov_b64_e32 v[44:45], 0
	v_mov_b64_e32 v[46:47], 0
	v_mov_b64_e32 v[56:57], 0
	v_mov_b64_e32 v[58:59], 0
	v_mov_b64_e32 v[60:61], 0
	v_mov_b64_e32 v[62:63], 0
	v_mov_b64_e32 v[64:65], 0
	v_mov_b64_e32 v[66:67], 0
	v_mov_b64_e32 v[68:69], 0
	v_mov_b64_e32 v[70:71], 0
	v_mov_b64_e32 v[80:81], 0
	v_mov_b64_e32 v[82:83], 0
	v_mov_b64_e32 v[84:85], 0
	v_mov_b64_e32 v[86:87], 0
	v_mov_b64_e32 v[96:97], 0
	v_mov_b64_e32 v[98:99], 0
	v_mov_b64_e32 v[100:101], 0
	v_mov_b64_e32 v[102:103], 0
	v_mov_b64_e32 v[112:113], 0
	v_mov_b64_e32 v[114:115], 0
	v_mov_b64_e32 v[116:117], 0
	v_mov_b64_e32 v[118:119], 0
	v_mov_b64_e32 v[72:73], 0
	v_mov_b64_e32 v[74:75], 0
	v_mov_b64_e32 v[76:77], 0
	v_mov_b64_e32 v[78:79], 0
	v_mov_b64_e32 v[88:89], 0
	v_mov_b64_e32 v[90:91], 0
	v_mov_b64_e32 v[92:93], 0
	v_mov_b64_e32 v[94:95], 0
	v_mov_b64_e32 v[104:105], 0
	v_mov_b64_e32 v[106:107], 0
	v_mov_b64_e32 v[108:109], 0
	v_mov_b64_e32 v[110:111], 0
	v_mov_b64_e32 v[120:121], 0
	v_mov_b64_e32 v[122:123], 0
	v_mov_b64_e32 v[124:125], 0
	v_mov_b64_e32 v[126:127], 0

.LBB0_641:
	s_ashr_i32 s29, s28, 31
	s_lshl_b64 s[30:31], s[28:29], 19
	s_add_u32 s30, s64, s30
	s_addc_u32 s31, s65, s31
	s_and_b64 s[34:35], s[8:9], exec
	s_cselect_b32 s42, s31, s7
	s_cselect_b32 s43, s30, s6
	s_ashr_i32 s23, s22, 31
	s_lshl_b64 s[34:35], s[22:23], 19
	s_add_u32 s34, s46, s34
	s_addc_u32 s35, s47, s35
	s_and_b64 s[40:41], s[8:9], exec
	s_cselect_b32 s23, s35, s39
	s_cselect_b32 s44, s34, s38
	s_add_u32 s6, s6, 0x40080
	s_addc_u32 s7, s7, 0
	s_add_u32 s45, s38, 0x100
	v_mov_b32_e32 v0, 0
	s_addc_u32 s67, s39, 0
	s_mov_b32 s68, -2
	s_waitcnt lgkmcnt(0)
	v_mov_b32_e32 v1, v0
	v_mov_b64_e32 v[2:3], 0
	v_mov_b64_e32 v[4:5], 0
	v_mov_b64_e32 v[6:7], 0
	v_mov_b64_e32 v[16:17], 0
	v_mov_b64_e32 v[18:19], 0
	v_mov_b64_e32 v[20:21], 0
	v_mov_b64_e32 v[22:23], 0
	v_mov_b64_e32 v[40:41], 0
	v_mov_b64_e32 v[42:43], 0
	v_mov_b64_e32 v[44:45], 0
	v_mov_b64_e32 v[46:47], 0
	v_mov_b64_e32 v[56:57], 0
	v_mov_b64_e32 v[58:59], 0
	v_mov_b64_e32 v[60:61], 0
	v_mov_b64_e32 v[62:63], 0
	v_mov_b64_e32 v[8:9], 0
	v_mov_b64_e32 v[10:11], 0
	v_mov_b64_e32 v[12:13], 0
	v_mov_b64_e32 v[14:15], 0
	v_mov_b64_e32 v[32:33], 0
	v_mov_b64_e32 v[34:35], 0
	v_mov_b64_e32 v[36:37], 0
	v_mov_b64_e32 v[38:39], 0
	v_mov_b64_e32 v[48:49], 0
	v_mov_b64_e32 v[50:51], 0
	v_mov_b64_e32 v[52:53], 0
	v_mov_b64_e32 v[54:55], 0
	v_mov_b64_e32 v[64:65], 0
	v_mov_b64_e32 v[66:67], 0
	v_mov_b64_e32 v[68:69], 0
	v_mov_b64_e32 v[70:71], 0
	v_mov_b64_e32 v[72:73], 0
	v_mov_b64_e32 v[74:75], 0
	v_mov_b64_e32 v[76:77], 0
	v_mov_b64_e32 v[78:79], 0
	v_mov_b64_e32 v[88:89], 0
	v_mov_b64_e32 v[90:91], 0
	v_mov_b64_e32 v[92:93], 0
	v_mov_b64_e32 v[94:95], 0
	v_mov_b64_e32 v[104:105], 0
	v_mov_b64_e32 v[106:107], 0
	v_mov_b64_e32 v[108:109], 0
	v_mov_b64_e32 v[110:111], 0
	v_mov_b64_e32 v[120:121], 0
	v_mov_b64_e32 v[122:123], 0
	v_mov_b64_e32 v[124:125], 0
	v_mov_b64_e32 v[126:127], 0
	v_mov_b64_e32 v[80:81], 0
	v_mov_b64_e32 v[82:83], 0
	v_mov_b64_e32 v[84:85], 0
	v_mov_b64_e32 v[86:87], 0
	v_mov_b64_e32 v[96:97], 0
	v_mov_b64_e32 v[98:99], 0
	v_mov_b64_e32 v[100:101], 0
	v_mov_b64_e32 v[102:103], 0
	v_mov_b64_e32 v[112:113], 0
	v_mov_b64_e32 v[114:115], 0
	v_mov_b64_e32 v[116:117], 0
	v_mov_b64_e32 v[118:119], 0
	v_mov_b64_e32 v[128:129], 0
	v_mov_b64_e32 v[130:131], 0
	v_mov_b64_e32 v[132:133], 0
	v_mov_b64_e32 v[134:135], 0

.LBB0_869:
	s_lshl_b64 s[28:29], s[20:21], 20
	s_add_u32 s28, s39, s28
	s_addc_u32 s29, s40, s29
	s_and_b64 s[0:1], s[0:1], exec
	s_cselect_b32 s21, s29, s37
	s_cselect_b32 s31, s28, s36
	s_add_u32 s71, s36, 0x100
	v_mov_b32_e32 v0, 0
	s_addc_u32 s78, s37, 0
	s_mov_b32 s79, -2
	v_mov_b32_e32 v1, v0
	v_mov_b64_e32 v[2:3], 0
	v_mov_b64_e32 v[4:5], 0
	v_mov_b64_e32 v[6:7], 0
	v_mov_b64_e32 v[12:13], 0
	v_mov_b64_e32 v[14:15], 0
	v_mov_b64_e32 v[20:21], 0
	v_mov_b64_e32 v[22:23], 0
	v_mov_b64_e32 v[24:25], 0
	v_mov_b64_e32 v[26:27], 0
	v_mov_b64_e32 v[28:29], 0
	v_mov_b64_e32 v[30:31], 0
	v_mov_b64_e32 v[32:33], 0
	v_mov_b64_e32 v[34:35], 0
	v_mov_b64_e32 v[36:37], 0
	v_mov_b64_e32 v[38:39], 0
	v_mov_b64_e32 v[40:41], 0
	v_mov_b64_e32 v[42:43], 0
	v_mov_b64_e32 v[44:45], 0
	v_mov_b64_e32 v[46:47], 0
	v_mov_b64_e32 v[48:49], 0
	v_mov_b64_e32 v[50:51], 0
	v_mov_b64_e32 v[52:53], 0
	v_mov_b64_e32 v[54:55], 0
	v_mov_b64_e32 v[56:57], 0
	v_mov_b64_e32 v[58:59], 0
	v_mov_b64_e32 v[60:61], 0
	v_mov_b64_e32 v[62:63], 0
	v_mov_b64_e32 v[64:65], 0
	v_mov_b64_e32 v[66:67], 0
	v_mov_b64_e32 v[68:69], 0
	v_mov_b64_e32 v[70:71], 0
	s_branch .LBB0_871

.LBB0_1550:
	s_ashr_i32 s13, s12, 31
	v_cmp_lt_i64_e32 vcc, s[14:15], v[164:165]
	s_lshl_b64 s[14:15], s[12:13], 19
	s_add_u32 s14, s26, s14
	s_addc_u32 s15, s27, s15
	s_and_b64 s[16:17], vcc, exec
	s_cselect_b32 s13, s15, s21
	s_cselect_b32 s19, s14, s20
	s_ashr_i32 s11, s10, 31
	s_lshl_b64 s[16:17], s[10:11], 19
	s_add_u32 s16, s31, s16
	s_addc_u32 s17, s34, s17
	s_and_b64 s[28:29], vcc, exec
	s_cselect_b32 s11, s17, s23
	s_cselect_b32 s48, s16, s22
	s_add_u32 s20, s20, 0x40080
	s_addc_u32 s21, s21, 0
	s_add_u32 s49, s22, 0x100
	v_mov_b32_e32 v0, 0
	s_addc_u32 s50, s23, 0
	s_mov_b32 s51, -2
	s_waitcnt lgkmcnt(0)
	v_mov_b32_e32 v1, v0
	v_mov_b64_e32 v[2:3], 0
	v_mov_b64_e32 v[4:5], 0
	v_mov_b64_e32 v[6:7], 0
	v_mov_b64_e32 v[16:17], 0
	v_mov_b64_e32 v[18:19], 0
	v_mov_b64_e32 v[20:21], 0
	v_mov_b64_e32 v[22:23], 0
	v_mov_b64_e32 v[32:33], 0
	v_mov_b64_e32 v[34:35], 0
	v_mov_b64_e32 v[36:37], 0
	v_mov_b64_e32 v[38:39], 0
	v_mov_b64_e32 v[48:49], 0
	v_mov_b64_e32 v[50:51], 0
	v_mov_b64_e32 v[52:53], 0
	v_mov_b64_e32 v[54:55], 0
	v_mov_b64_e32 v[8:9], 0
	v_mov_b64_e32 v[10:11], 0
	v_mov_b64_e32 v[12:13], 0
	v_mov_b64_e32 v[14:15], 0
	v_mov_b64_e32 v[24:25], 0
	v_mov_b64_e32 v[26:27], 0
	v_mov_b64_e32 v[28:29], 0
	v_mov_b64_e32 v[30:31], 0
	v_mov_b64_e32 v[40:41], 0
	v_mov_b64_e32 v[42:43], 0
	v_mov_b64_e32 v[44:45], 0
	v_mov_b64_e32 v[46:47], 0
	v_mov_b64_e32 v[56:57], 0
	v_mov_b64_e32 v[58:59], 0
	v_mov_b64_e32 v[60:61], 0
	v_mov_b64_e32 v[62:63], 0
	v_mov_b64_e32 v[64:65], 0
	v_mov_b64_e32 v[66:67], 0
	v_mov_b64_e32 v[68:69], 0
	v_mov_b64_e32 v[70:71], 0
	v_mov_b64_e32 v[80:81], 0
	v_mov_b64_e32 v[82:83], 0
	v_mov_b64_e32 v[84:85], 0
	v_mov_b64_e32 v[86:87], 0
	v_mov_b64_e32 v[96:97], 0
	v_mov_b64_e32 v[98:99], 0
	v_mov_b64_e32 v[100:101], 0
	v_mov_b64_e32 v[102:103], 0
	v_mov_b64_e32 v[112:113], 0
	v_mov_b64_e32 v[114:115], 0
	v_mov_b64_e32 v[116:117], 0
	v_mov_b64_e32 v[118:119], 0
	v_mov_b64_e32 v[72:73], 0
	v_mov_b64_e32 v[74:75], 0
	v_mov_b64_e32 v[76:77], 0
	v_mov_b64_e32 v[78:79], 0
	v_mov_b64_e32 v[88:89], 0
	v_mov_b64_e32 v[90:91], 0
	v_mov_b64_e32 v[92:93], 0
	v_mov_b64_e32 v[94:95], 0
	v_mov_b64_e32 v[104:105], 0
	v_mov_b64_e32 v[106:107], 0
	v_mov_b64_e32 v[108:109], 0
	v_mov_b64_e32 v[110:111], 0
	v_mov_b64_e32 v[120:121], 0
	v_mov_b64_e32 v[122:123], 0
	v_mov_b64_e32 v[124:125], 0
	v_mov_b64_e32 v[126:127], 0

.LBB0_1740:
	s_add_u32 s45, s16, 0x100
	v_mov_b32_e32 v0, 0
	s_addc_u32 s46, s17, 0
	s_mov_b32 s47, -2
	s_waitcnt lgkmcnt(0)
	v_mov_b32_e32 v1, v0
	v_mov_b64_e32 v[2:3], 0
	v_mov_b64_e32 v[4:5], 0
	v_mov_b64_e32 v[6:7], 0
	v_mov_b64_e32 v[16:17], 0
	v_mov_b64_e32 v[18:19], 0
	v_mov_b64_e32 v[20:21], 0
	v_mov_b64_e32 v[22:23], 0
	v_mov_b64_e32 v[32:33], 0
	v_mov_b64_e32 v[34:35], 0
	v_mov_b64_e32 v[36:37], 0
	v_mov_b64_e32 v[38:39], 0
	v_mov_b64_e32 v[48:49], 0
	v_mov_b64_e32 v[50:51], 0
	v_mov_b64_e32 v[52:53], 0
	v_mov_b64_e32 v[54:55], 0
	v_mov_b64_e32 v[8:9], 0
	v_mov_b64_e32 v[10:11], 0
	v_mov_b64_e32 v[12:13], 0
	v_mov_b64_e32 v[14:15], 0
	v_mov_b64_e32 v[24:25], 0
	v_mov_b64_e32 v[26:27], 0
	v_mov_b64_e32 v[28:29], 0
	v_mov_b64_e32 v[30:31], 0
	v_mov_b64_e32 v[40:41], 0
	v_mov_b64_e32 v[42:43], 0
	v_mov_b64_e32 v[44:45], 0
	v_mov_b64_e32 v[46:47], 0
	v_mov_b64_e32 v[56:57], 0
	v_mov_b64_e32 v[58:59], 0
	v_mov_b64_e32 v[60:61], 0
	v_mov_b64_e32 v[62:63], 0
	v_mov_b64_e32 v[64:65], 0
	v_mov_b64_e32 v[66:67], 0
	v_mov_b64_e32 v[68:69], 0
	v_mov_b64_e32 v[70:71], 0
	v_mov_b64_e32 v[80:81], 0
	v_mov_b64_e32 v[82:83], 0
	v_mov_b64_e32 v[84:85], 0
	v_mov_b64_e32 v[86:87], 0
	v_mov_b64_e32 v[96:97], 0
	v_mov_b64_e32 v[98:99], 0
	v_mov_b64_e32 v[100:101], 0
	v_mov_b64_e32 v[102:103], 0
	v_mov_b64_e32 v[112:113], 0
	v_mov_b64_e32 v[114:115], 0
	v_mov_b64_e32 v[116:117], 0
	v_mov_b64_e32 v[118:119], 0
	v_mov_b64_e32 v[72:73], 0
	v_mov_b64_e32 v[74:75], 0
	v_mov_b64_e32 v[76:77], 0
	v_mov_b64_e32 v[78:79], 0
	v_mov_b64_e32 v[88:89], 0
	v_mov_b64_e32 v[90:91], 0
	v_mov_b64_e32 v[92:93], 0
	v_mov_b64_e32 v[94:95], 0
	v_mov_b64_e32 v[104:105], 0
	v_mov_b64_e32 v[106:107], 0
	v_mov_b64_e32 v[108:109], 0
	v_mov_b64_e32 v[110:111], 0
	v_mov_b64_e32 v[120:121], 0
	v_mov_b64_e32 v[122:123], 0
	v_mov_b64_e32 v[124:125], 0
	v_mov_b64_e32 v[126:127], 0
